# W_out and down GEMM epilogues: the per-row sum-of-squares reductions through v_permlane16_swap / v_permlane32_swap instead of ds_bpermute + lgkmcnt(0) waits (the final add moved in front of the exec m
# baseline (speedup 1.0000x reference)
; __device__ __forceinline__ void ss_add(ss_t* p, float sq) { const float fl = floorf(sq); const unsigned hi = (unsigned)fl, lo = (unsigned)((sq - fl) * 4294967296.0f); atomicAdd(p, ((ss_t)hi << 32) | (ss_t)lo); }
;     __device__ __forceinline__ void operator()(const f32x4 (&acc)[2][2][4][2], const Unit& u, int wr, int wc, int fr, int fq) const {
;         int row0 = u.pm * BM + wr * 64 + fr; asm volatile("" : "+v"(row0));     const int col0 = u.pn * BM + wc * 32 + 8 * fq;
; #pragma unroll
;         for (int ai = 0; ai < 2; ++ai) {
;             u32x4 res[4][2];
; #pragma unroll
;             for (int m = 0; m < 4; ++m) { const bf16_t* rowp = XB + (size_t)(row0 + ai * HALF + m * 16) * ldc + col0;
; #pragma unroll
;                 for (int bj = 0; bj < 2; ++bj) res[m][bj] = *(const u32x4*)(rowp + bj * HALF); }
;             asm volatile("" ::: "memory");
; #pragma unroll
;             for (int m = 0; m < 4; ++m) { const int row = row0 + ai * HALF + m * 16; const size_t off = (size_t)row * ldc + col0;
;                 float rs = 1.0f; if (KS) rs = 1.0f / sqrtf(ss_get(ssb + row) * (1.0f / 1024.f) + 1e-6f);
;                 float sq = 0.f;
; #pragma unroll
;                 for (int bj = 0; bj < 2; ++bj) { const u32x4 r = res[m][bj];
;                     const f32x4 x0 = (f32x4){__uint_as_float(r.x << 16), __uint_as_float(r.x & 0xffff0000u), __uint_as_float(r.y << 16), __uint_as_float(r.y & 0xffff0000u)};
;                     const f32x4 x1 = (f32x4){__uint_as_float(r.z << 16), __uint_as_float(r.z & 0xffff0000u), __uint_as_float(r.w << 16), __uint_as_float(r.w & 0xffff0000u)};
;                     const f32x4 v0 = x0 + acc[ai][bj][m][0] * rs, v1 = x1 + acc[ai][bj][m][1] * rs;
;                     if (OUT) { *(f32x4*)(OUT + off + bj * HALF) = v0; *(f32x4*)(OUT + off + bj * HALF + 4) = v1; }
;                     else { sq += ((v0[0] * v0[0] + v0[1] * v0[1]) + (v0[2] * v0[2] + v0[3] * v0[3])) + ((v1[0] * v1[0] + v1[1] * v1[1]) + (v1[2] * v1[2] + v1[3] * v1[3]));
;                         u32x4 w; w.x = pkbf(v0[0], v0[1]); w.y = pkbf(v0[2], v0[3]); w.z = pkbf(v1[0], v1[1]); w.w = pkbf(v1[2], v1[3]); *(u32x4*)(XB + off + bj * HALF) = w; } }
;                 if (!OUT) { sq += __shfl_xor(sq, 16); sq += __shfl_xor(sq, 32); if (fq == 0) ss_add(ssq_out + row, sq); } }
.LBB0_931:
	v_lshl_or_b32 v0, s60, 8, v194
	v_mov_b32_e32 v182, v193
	v_ashrrev_i32_e32 v1, 31, v0
	v_lshlrev_b64 v[212:213], 1, v[0:1]
	v_ashrrev_i32_e32 v183, 31, v182
	v_lshl_add_u64 v[184:185], s[64:65], 0, v[212:213]
	v_lshlrev_b64 v[214:215], 12, v[182:183]
	v_add_u32_e32 v190, 16, v182
	v_lshl_add_u64 v[132:133], v[184:185], 0, v[214:215]
	v_ashrrev_i32_e32 v191, 31, v190
	global_load_dwordx4 v[196:199], v[132:133], off
	global_load_dwordx4 v[200:203], v[132:133], off offset:256
	v_lshlrev_b64 v[132:133], 12, v[190:191]
	v_add_u32_e32 v188, 32, v182
	v_lshl_add_u64 v[132:133], v[184:185], 0, v[132:133]
	v_ashrrev_i32_e32 v189, 31, v188
	global_load_dwordx4 v[152:155], v[132:133], off
	global_load_dwordx4 v[148:151], v[132:133], off offset:256
	v_lshlrev_b64 v[132:133], 12, v[188:189]
	v_add_u32_e32 v186, 48, v182
	v_lshl_add_u64 v[132:133], v[184:185], 0, v[132:133]
	v_ashrrev_i32_e32 v187, 31, v186
	global_load_dwordx4 v[144:147], v[132:133], off
	global_load_dwordx4 v[140:143], v[132:133], off offset:256
	v_lshlrev_b64 v[132:133], 12, v[186:187]
	v_lshl_add_u64 v[132:133], v[184:185], 0, v[132:133]
	global_load_dwordx4 v[136:139], v[132:133], off
	s_nop 0
	global_load_dwordx4 v[132:135], v[132:133], off offset:256
	v_lshl_add_u64 v[180:181], v[182:183], 3, s[8:9]
	s_flbit_i32_b32 s2, 0
	v_mov_b32_e32 v219, v2
	s_min_u32 s43, s2, 32
	s_sub_i32 s46, 32, s43
	s_waitcnt vmcnt(0)
	v_and_b32_e32 v221, 0xffff0000, v198
	v_mov_b32_e32 v216, v240
	s_nop 0
	s_nop 0
	s_nop 0
	s_nop 1
	s_nop 1
	s_nop 0
	v_lshlrev_b32_e32 v218, 16, v196
	v_and_b32_e32 v219, 0xffff0000, v196
	v_lshlrev_b32_e32 v196, 16, v197
	v_and_b32_e32 v197, 0xffff0000, v197
	v_lshlrev_b32_e32 v220, 16, v198
	v_lshlrev_b32_e32 v198, 16, v199
	v_and_b32_e32 v199, 0xffff0000, v199
	v_pk_fma_f32 v[130:131], v[130:131], v[216:217], v[196:197] op_sel_hi:[1,0,1]
	v_pk_fma_f32 v[128:129], v[128:129], v[216:217], v[218:219] op_sel_hi:[1,0,1]
	v_pk_fma_f32 v[196:197], v[126:127], v[216:217], v[198:199] op_sel_hi:[1,0,1]
	v_pk_fma_f32 v[126:127], v[124:125], v[216:217], v[220:221] op_sel_hi:[1,0,1]
	v_mul_f32_e32 v3, v129, v129
	v_mul_f32_e32 v124, v131, v131
	v_fmac_f32_e32 v3, v128, v128
	v_fmac_f32_e32 v124, v130, v130
	v_add_f32_e32 v3, v3, v124
	v_mul_f32_e32 v124, v127, v127
	v_mul_f32_e32 v125, v197, v197
	v_fmac_f32_e32 v124, v126, v126
	v_fmac_f32_e32 v125, v196, v196
	v_add_f32_e32 v124, v124, v125
	v_add_f32_e32 v3, v3, v124
	v_cvt_pk_bf16_f32 v124, v128, v129
	v_lshl_add_u64 v[128:129], s[64:65], 0, v[214:215]
	v_cvt_pk_bf16_f32 v125, v130, v131
	v_cvt_pk_bf16_f32 v126, v126, v127
	v_cvt_pk_bf16_f32 v127, v196, v197
	v_lshl_add_u64 v[128:129], v[128:129], 0, v[212:213]
	global_store_dwordx4 v[128:129], v[124:127], off
	v_lshlrev_b32_e32 v130, 16, v202
	v_and_b32_e32 v131, 0xffff0000, v202
	v_lshlrev_b32_e32 v124, 16, v200
	v_and_b32_e32 v125, 0xffff0000, v200
	v_lshlrev_b32_e32 v126, 16, v201
	v_and_b32_e32 v127, 0xffff0000, v201
	v_pk_fma_f32 v[122:123], v[122:123], v[216:217], v[126:127] op_sel_hi:[1,0,1]
	v_pk_fma_f32 v[120:121], v[120:121], v[216:217], v[124:125] op_sel_hi:[1,0,1]
	v_lshlrev_b32_e32 v196, 16, v203
	v_and_b32_e32 v197, 0xffff0000, v203
	v_pk_fma_f32 v[126:127], v[116:117], v[216:217], v[130:131] op_sel_hi:[1,0,1]
	v_mul_f32_e32 v116, v121, v121
	v_mul_f32_e32 v117, v123, v123
	v_pk_fma_f32 v[124:125], v[118:119], v[216:217], v[196:197] op_sel_hi:[1,0,1]
	v_fmac_f32_e32 v116, v120, v120
	v_fmac_f32_e32 v117, v122, v122
	v_add_f32_e32 v116, v116, v117
	v_mul_f32_e32 v117, v127, v127
	v_mul_f32_e32 v118, v125, v125
	v_fmac_f32_e32 v117, v126, v126
	v_fmac_f32_e32 v118, v124, v124
	v_add_f32_e32 v117, v117, v118
	v_add_f32_e32 v116, v116, v117
	v_and_b32_e32 v117, 64, v208
	v_add_f32_e32 v116, v3, v116
	v_xor_b32_e32 v3, 16, v208
	v_add_u32_e32 v117, 64, v117
	v_cmp_lt_i32_e32 vcc, v3, v117
	v_cvt_pk_bf16_f32 v118, v120, v121
	v_cvt_pk_bf16_f32 v119, v122, v123
	v_cndmask_b32_e32 v3, v208, v3, vcc
	v_cvt_pk_bf16_f32 v120, v126, v127
	v_cvt_pk_bf16_f32 v121, v124, v125
	v_lshlrev_b32_e32 v3, 2, v3
	global_store_dwordx4 v[128:129], v[118:121], off offset:256
	s_nop 1
	v_mov_b32_e32 v118, v116
	s_nop 1
	v_permlane16_swap_b32_e32 v116, v118
	s_nop 0
	v_add_f32_e32 v116, v116, v118
	v_xor_b32_e32 v118, 32, v208
	v_cmp_lt_i32_e32 vcc, v118, v117
	s_nop 1
	v_cndmask_b32_e32 v117, v208, v118, vcc
	v_lshlrev_b32_e32 v117, 2, v117
	v_mov_b32_e32 v118, v116
	s_nop 1
	v_permlane32_swap_b32_e32 v116, v118
	v_add_f32_e32 v116, v116, v118
	s_and_saveexec_b64 s[2:3], s[40:41]
	s_cbranch_execz .LBB0_933
	s_nop 0
	v_floor_f32_e32 v118, v116
	v_sub_f32_e32 v116, v116, v118
	v_mul_f32_e32 v116, 0x4f800000, v116
	v_cvt_u32_f32_e32 v119, v118
	v_cvt_u32_f32_e32 v118, v116
	v_lshl_add_u64 v[120:121], v[182:183], 3, s[4:5]
	global_atomic_add_x2 v[120:121], v[118:119], off
; __device__ __forceinline__ void ss_add(ss_t* p, float sq) { const float fl = floorf(sq); const unsigned hi = (unsigned)fl, lo = (unsigned)((sq - fl) * 4294967296.0f); atomicAdd(p, ((ss_t)hi << 32) | (ss_t)lo); }
; __device__ __forceinline__ float ss_get(const ss_t* p) { const ss_t v = *p; return (float)(unsigned)(v >> 32) + (float)(unsigned)v * 2.3283064365386963e-10f; }
; __device__ __forceinline__ unsigned pkbf(float lo, float hi) { typedef float f2_t __attribute__((ext_vector_type(2))); typedef __bf16 b2_t __attribute__((ext_vector_type(2))); f2_t v = {lo, hi}; b2_t b = __builtin_convertvector(v, b2_t); return __builtin_bit_cast(unsigned, b); }
;     __device__ __forceinline__ void operator()(const f32x4 (&acc)[2][2][4][2], const Unit& u, int wr, int wc, int fr, int fq) const {
;     ...
;             for (int m = 0; m < 4; ++m) { const int row = row0 + ai * HALF + m * 16; const size_t off = (size_t)row * ldc + col0;
;                 float rs = 1.0f; if (KS) rs = 1.0f / sqrtf(ss_get(ssb + row) * (1.0f / 1024.f) + 1e-6f);
;                 float sq = 0.f;
; #pragma unroll
;                 for (int bj = 0; bj < 2; ++bj) { const u32x4 r = res[m][bj];
;                     const f32x4 x0 = (f32x4){__uint_as_float(r.x << 16), __uint_as_float(r.x & 0xffff0000u), __uint_as_float(r.y << 16), __uint_as_float(r.y & 0xffff0000u)};
;                     const f32x4 x1 = (f32x4){__uint_as_float(r.z << 16), __uint_as_float(r.z & 0xffff0000u), __uint_as_float(r.w << 16), __uint_as_float(r.w & 0xffff0000u)};
;                     const f32x4 v0 = x0 + acc[ai][bj][m][0] * rs, v1 = x1 + acc[ai][bj][m][1] * rs;
;                     if (OUT) { *(f32x4*)(OUT + off + bj * HALF) = v0; *(f32x4*)(OUT + off + bj * HALF + 4) = v1; }
;                     else { sq += ((v0[0] * v0[0] + v0[1] * v0[1]) + (v0[2] * v0[2] + v0[3] * v0[3])) + ((v1[0] * v1[0] + v1[1] * v1[1]) + (v1[2] * v1[2] + v1[3] * v1[3]));
;                         u32x4 w; w.x = pkbf(v0[0], v0[1]); w.y = pkbf(v0[2], v0[3]); w.z = pkbf(v1[0], v1[1]); w.w = pkbf(v1[2], v1[3]); *(u32x4*)(XB + off + bj * HALF) = w; } }
;                 if (!OUT) { sq += __shfl_xor(sq, 16); sq += __shfl_xor(sq, 32); if (fq == 0) ss_add(ssq_out + row, sq); } }
.LBB0_933:
	s_or_b64 exec, exec, s[2:3]
	s_nop 0
	v_mov_b32_e32 v123, v2
	v_lshlrev_b32_e32 v126, 16, v155
	v_and_b32_e32 v127, 0xffff0000, v155
	v_and_b32_e32 v125, 0xffff0000, v154
	s_waitcnt lgkmcnt(0)
	v_lshlrev_b64 v[118:119], 11, v[190:191]
	v_mov_b32_e32 v116, v241
	s_nop 0
	s_nop 0
	s_nop 0
	s_nop 1
	s_nop 1
	s_nop 0
	v_lshlrev_b32_e32 v120, 16, v152
	v_and_b32_e32 v121, 0xffff0000, v152
	v_lshlrev_b32_e32 v122, 16, v153
	v_and_b32_e32 v123, 0xffff0000, v153
	v_pk_fma_f32 v[114:115], v[114:115], v[116:117], v[122:123] op_sel_hi:[1,0,1]
	v_pk_fma_f32 v[112:113], v[112:113], v[116:117], v[120:121] op_sel_hi:[1,0,1]
	v_lshlrev_b32_e32 v124, 16, v154
	v_pk_fma_f32 v[120:121], v[110:111], v[116:117], v[126:127] op_sel_hi:[1,0,1]
	v_mul_f32_e32 v110, v113, v113
	v_mul_f32_e32 v111, v115, v115
	v_pk_fma_f32 v[108:109], v[108:109], v[116:117], v[124:125] op_sel_hi:[1,0,1]
	v_fmac_f32_e32 v110, v112, v112
	v_fmac_f32_e32 v111, v114, v114
	v_add_f32_e32 v110, v110, v111
	v_mul_f32_e32 v111, v109, v109
	v_mul_f32_e32 v122, v121, v121
	v_fmac_f32_e32 v111, v108, v108
	v_fmac_f32_e32 v122, v120, v120
	v_add_f32_e32 v111, v111, v122
	v_add_f32_e32 v122, v110, v111
	v_cvt_pk_bf16_f32 v110, v112, v113
	v_cvt_pk_bf16_f32 v112, v108, v109
	v_lshl_add_u64 v[108:109], v[118:119], 1, s[64:65]
	v_cvt_pk_bf16_f32 v111, v114, v115
	v_cvt_pk_bf16_f32 v113, v120, v121
	v_lshl_add_u64 v[108:109], v[0:1], 1, v[108:109]
	global_store_dwordx4 v[108:109], v[110:113], off
	v_lshlrev_b32_e32 v114, 16, v150
	v_and_b32_e32 v115, 0xffff0000, v150
	v_lshlrev_b32_e32 v110, 16, v148
	v_and_b32_e32 v111, 0xffff0000, v148
	v_lshlrev_b32_e32 v112, 16, v149
	v_and_b32_e32 v113, 0xffff0000, v149
	v_lshlrev_b32_e32 v118, 16, v151
	v_and_b32_e32 v119, 0xffff0000, v151
	v_pk_fma_f32 v[106:107], v[106:107], v[116:117], v[112:113] op_sel_hi:[1,0,1]
	v_pk_fma_f32 v[104:105], v[104:105], v[116:117], v[110:111] op_sel_hi:[1,0,1]
	v_pk_fma_f32 v[110:111], v[102:103], v[116:117], v[118:119] op_sel_hi:[1,0,1]
	v_pk_fma_f32 v[102:103], v[100:101], v[116:117], v[114:115] op_sel_hi:[1,0,1]
	v_mul_f32_e32 v100, v105, v105
	v_mul_f32_e32 v101, v107, v107
	v_fmac_f32_e32 v100, v104, v104
	v_fmac_f32_e32 v101, v106, v106
	v_add_f32_e32 v100, v100, v101
	v_mul_f32_e32 v101, v103, v103
	v_mul_f32_e32 v112, v111, v111
	v_fmac_f32_e32 v101, v102, v102
	v_fmac_f32_e32 v112, v110, v110
	v_add_f32_e32 v101, v101, v112
	v_add_f32_e32 v100, v100, v101
	v_add_f32_e32 v112, v122, v100
	v_cvt_pk_bf16_f32 v100, v104, v105
	v_cvt_pk_bf16_f32 v101, v106, v107
	v_cvt_pk_bf16_f32 v102, v102, v103
	v_cvt_pk_bf16_f32 v103, v110, v111
	global_store_dwordx4 v[108:109], v[100:103], off offset:256
	s_nop 1
	v_mov_b32_e32 v100, v112
	s_nop 1
	v_permlane16_swap_b32_e32 v112, v100
	s_nop 0
	v_add_f32_e32 v100, v112, v100
	v_mov_b32_e32 v101, v100
	s_nop 1
	v_permlane32_swap_b32_e32 v100, v101
	v_add_f32_e32 v102, v100, v101
	s_and_saveexec_b64 s[2:3], s[40:41]
	s_cbranch_execz .LBB0_935
	s_nop 0
	v_floor_f32_e32 v104, v102
	v_sub_f32_e32 v102, v102, v104
	v_mul_f32_e32 v102, 0x4f800000, v102
	v_cvt_u32_f32_e32 v103, v104
	v_cvt_u32_f32_e32 v102, v102
	v_lshl_add_u64 v[100:101], v[190:191], 3, s[4:5]
	global_atomic_add_x2 v[100:101], v[102:103], off
.LBB0_935:
	s_or_b64 exec, exec, s[2:3]
	s_waitcnt lgkmcnt(0)
	s_nop 0
	v_mov_b32_e32 v105, v2
	v_lshlrev_b32_e32 v110, 16, v147
	v_and_b32_e32 v111, 0xffff0000, v147
	v_lshlrev_b32_e32 v108, 16, v146
	v_and_b32_e32 v109, 0xffff0000, v146
	v_lshlrev_b64 v[102:103], 11, v[188:189]
	v_mov_b32_e32 v100, v242
	s_nop 0
	s_nop 0
	s_nop 0
	s_nop 1
	s_nop 1
	s_nop 0
	v_lshlrev_b32_e32 v104, 16, v144
	v_and_b32_e32 v105, 0xffff0000, v144
	v_lshlrev_b32_e32 v106, 16, v145
	v_and_b32_e32 v107, 0xffff0000, v145
	v_pk_fma_f32 v[98:99], v[98:99], v[100:101], v[106:107] op_sel_hi:[1,0,1]
	v_pk_fma_f32 v[96:97], v[96:97], v[100:101], v[104:105] op_sel_hi:[1,0,1]
	v_pk_fma_f32 v[104:105], v[94:95], v[100:101], v[110:111] op_sel_hi:[1,0,1]
	v_mul_f32_e32 v94, v97, v97
	v_mul_f32_e32 v95, v99, v99
	v_pk_fma_f32 v[92:93], v[92:93], v[100:101], v[108:109] op_sel_hi:[1,0,1]
	v_fmac_f32_e32 v94, v96, v96
	v_fmac_f32_e32 v95, v98, v98
	v_add_f32_e32 v94, v94, v95
	v_mul_f32_e32 v95, v93, v93
	v_mul_f32_e32 v101, v105, v105
	v_fmac_f32_e32 v95, v92, v92
	v_fmac_f32_e32 v101, v104, v104
	v_add_f32_e32 v95, v95, v101
	v_add_f32_e32 v101, v94, v95
	v_cvt_pk_bf16_f32 v94, v96, v97
	v_cvt_pk_bf16_f32 v96, v92, v93
	v_lshl_add_u64 v[92:93], v[102:103], 1, s[64:65]
	v_cvt_pk_bf16_f32 v95, v98, v99
	v_cvt_pk_bf16_f32 v97, v104, v105
	v_lshl_add_u64 v[92:93], v[0:1], 1, v[92:93]
	global_store_dwordx4 v[92:93], v[94:97], off
	v_lshlrev_b32_e32 v98, 16, v142
	v_and_b32_e32 v99, 0xffff0000, v142
	v_lshlrev_b32_e32 v94, 16, v140
	v_and_b32_e32 v95, 0xffff0000, v140
	v_lshlrev_b32_e32 v96, 16, v141
	v_and_b32_e32 v97, 0xffff0000, v141
	v_lshlrev_b32_e32 v102, 16, v143
	v_and_b32_e32 v103, 0xffff0000, v143
	v_pk_fma_f32 v[90:91], v[90:91], v[100:101], v[96:97] op_sel_hi:[1,0,1]
	v_pk_fma_f32 v[88:89], v[88:89], v[100:101], v[94:95] op_sel_hi:[1,0,1]
	v_pk_fma_f32 v[94:95], v[86:87], v[100:101], v[102:103] op_sel_hi:[1,0,1]
	v_pk_fma_f32 v[86:87], v[84:85], v[100:101], v[98:99] op_sel_hi:[1,0,1]
	v_mul_f32_e32 v84, v89, v89
	v_mul_f32_e32 v85, v91, v91
	v_fmac_f32_e32 v84, v88, v88
	v_fmac_f32_e32 v85, v90, v90
	v_add_f32_e32 v84, v84, v85
	v_mul_f32_e32 v85, v87, v87
	v_mul_f32_e32 v96, v95, v95
	v_fmac_f32_e32 v85, v86, v86
	v_fmac_f32_e32 v96, v94, v94
	v_add_f32_e32 v85, v85, v96
	v_add_f32_e32 v84, v84, v85
	v_add_f32_e32 v96, v101, v84
	v_cvt_pk_bf16_f32 v84, v88, v89
	v_cvt_pk_bf16_f32 v85, v90, v91
	v_cvt_pk_bf16_f32 v86, v86, v87
	v_cvt_pk_bf16_f32 v87, v94, v95
	global_store_dwordx4 v[92:93], v[84:87], off offset:256
	s_nop 1
	v_mov_b32_e32 v84, v96
	s_nop 1
	v_permlane16_swap_b32_e32 v96, v84
	s_nop 0
	v_add_f32_e32 v84, v96, v84
	v_mov_b32_e32 v85, v84
	s_nop 1
	v_permlane32_swap_b32_e32 v84, v85
	v_add_f32_e32 v86, v84, v85
	s_and_saveexec_b64 s[2:3], s[40:41]
	s_cbranch_execz .LBB0_937
	s_nop 0
	v_floor_f32_e32 v88, v86
	v_sub_f32_e32 v86, v86, v88
	v_mul_f32_e32 v86, 0x4f800000, v86
	v_cvt_u32_f32_e32 v87, v88
	v_cvt_u32_f32_e32 v86, v86
	v_lshl_add_u64 v[84:85], v[188:189], 3, s[4:5]
	global_atomic_add_x2 v[84:85], v[86:87], off
; __device__ __forceinline__ void ss_add(ss_t* p, float sq) { const float fl = floorf(sq); const unsigned hi = (unsigned)fl, lo = (unsigned)((sq - fl) * 4294967296.0f); atomicAdd(p, ((ss_t)hi << 32) | (ss_t)lo); }
; __device__ __forceinline__ float ss_get(const ss_t* p) { const ss_t v = *p; return (float)(unsigned)(v >> 32) + (float)(unsigned)v * 2.3283064365386963e-10f; }
;     __device__ __forceinline__ void operator()(const f32x4 (&acc)[2][2][4][2], const Unit& u, int wr, int wc, int fr, int fq) const {
;     ...
;             for (int m = 0; m < 4; ++m) { const bf16_t* rowp = XB + (size_t)(row0 + ai * HALF + m * 16) * ldc + col0;
; #pragma unroll
;                 for (int bj = 0; bj < 2; ++bj) res[m][bj] = *(const u32x4*)(rowp + bj * HALF); }
;             asm volatile("" ::: "memory");
; #pragma unroll
;             for (int m = 0; m < 4; ++m) { const int row = row0 + ai * HALF + m * 16; const size_t off = (size_t)row * ldc + col0;
;                 float rs = 1.0f; if (KS) rs = 1.0f / sqrtf(ss_get(ssb + row) * (1.0f / 1024.f) + 1e-6f);
;                 float sq = 0.f;
; #pragma unroll
;                 for (int bj = 0; bj < 2; ++bj) { const u32x4 r = res[m][bj];
;                     const f32x4 x0 = (f32x4){__uint_as_float(r.x << 16), __uint_as_float(r.x & 0xffff0000u), __uint_as_float(r.y << 16), __uint_as_float(r.y & 0xffff0000u)};
;                     const f32x4 x1 = (f32x4){__uint_as_float(r.z << 16), __uint_as_float(r.z & 0xffff0000u), __uint_as_float(r.w << 16), __uint_as_float(r.w & 0xffff0000u)};
;                     const f32x4 v0 = x0 + acc[ai][bj][m][0] * rs, v1 = x1 + acc[ai][bj][m][1] * rs;
;                     if (OUT) { *(f32x4*)(OUT + off + bj * HALF) = v0; *(f32x4*)(OUT + off + bj * HALF + 4) = v1; }
;                     else { sq += ((v0[0] * v0[0] + v0[1] * v0[1]) + (v0[2] * v0[2] + v0[3] * v0[3])) + ((v1[0] * v1[0] + v1[1] * v1[1]) + (v1[2] * v1[2] + v1[3] * v1[3]));
;                         u32x4 w; w.x = pkbf(v0[0], v0[1]); w.y = pkbf(v0[2], v0[3]); w.z = pkbf(v1[0], v1[1]); w.w = pkbf(v1[2], v1[3]); *(u32x4*)(XB + off + bj * HALF) = w; } }
;                 if (!OUT) { sq += __shfl_xor(sq, 16); sq += __shfl_xor(sq, 32); if (fq == 0) ss_add(ssq_out + row, sq); } }
.LBB0_937:
	s_or_b64 exec, exec, s[2:3]
	s_waitcnt lgkmcnt(0)
	s_nop 0
	v_mov_b32_e32 v89, v2
	v_lshlrev_b32_e32 v94, 16, v139
	v_and_b32_e32 v95, 0xffff0000, v139
	v_lshlrev_b32_e32 v92, 16, v138
	v_and_b32_e32 v93, 0xffff0000, v138
	v_lshlrev_b64 v[86:87], 11, v[186:187]
	v_mov_b32_e32 v84, v243
	s_nop 0
	s_nop 0
	s_nop 0
	s_nop 1
	s_nop 1
	s_nop 0
	v_lshlrev_b32_e32 v88, 16, v136
	v_and_b32_e32 v89, 0xffff0000, v136
	v_lshlrev_b32_e32 v90, 16, v137
	v_and_b32_e32 v91, 0xffff0000, v137
	v_pk_fma_f32 v[82:83], v[82:83], v[84:85], v[90:91] op_sel_hi:[1,0,1]
	v_pk_fma_f32 v[80:81], v[80:81], v[84:85], v[88:89] op_sel_hi:[1,0,1]
	v_pk_fma_f32 v[88:89], v[78:79], v[84:85], v[94:95] op_sel_hi:[1,0,1]
	v_mul_f32_e32 v78, v81, v81
	v_mul_f32_e32 v79, v83, v83
	v_pk_fma_f32 v[76:77], v[76:77], v[84:85], v[92:93] op_sel_hi:[1,0,1]
	v_fmac_f32_e32 v78, v80, v80
	v_fmac_f32_e32 v79, v82, v82
	v_add_f32_e32 v78, v78, v79
	v_mul_f32_e32 v79, v77, v77
	v_mul_f32_e32 v85, v89, v89
	v_fmac_f32_e32 v79, v76, v76
	v_fmac_f32_e32 v85, v88, v88
	v_add_f32_e32 v79, v79, v85
	v_add_f32_e32 v85, v78, v79
	v_cvt_pk_bf16_f32 v78, v80, v81
	v_cvt_pk_bf16_f32 v80, v76, v77
	v_lshl_add_u64 v[76:77], v[86:87], 1, s[64:65]
	v_cvt_pk_bf16_f32 v79, v82, v83
	v_cvt_pk_bf16_f32 v81, v88, v89
	v_lshl_add_u64 v[76:77], v[0:1], 1, v[76:77]
	global_store_dwordx4 v[76:77], v[78:81], off
	v_lshlrev_b32_e32 v82, 16, v134
	v_and_b32_e32 v83, 0xffff0000, v134
	v_lshlrev_b32_e32 v78, 16, v132
	v_and_b32_e32 v79, 0xffff0000, v132
	v_lshlrev_b32_e32 v80, 16, v133
	v_and_b32_e32 v81, 0xffff0000, v133
	v_lshlrev_b32_e32 v86, 16, v135
	v_and_b32_e32 v87, 0xffff0000, v135
	v_pk_fma_f32 v[74:75], v[74:75], v[84:85], v[80:81] op_sel_hi:[1,0,1]
	v_pk_fma_f32 v[72:73], v[72:73], v[84:85], v[78:79] op_sel_hi:[1,0,1]
	v_pk_fma_f32 v[78:79], v[70:71], v[84:85], v[86:87] op_sel_hi:[1,0,1]
	v_pk_fma_f32 v[70:71], v[68:69], v[84:85], v[82:83] op_sel_hi:[1,0,1]
	v_mul_f32_e32 v68, v73, v73
	v_mul_f32_e32 v69, v75, v75
	v_fmac_f32_e32 v68, v72, v72
	v_fmac_f32_e32 v69, v74, v74
	v_add_f32_e32 v68, v68, v69
	v_mul_f32_e32 v69, v71, v71
	v_mul_f32_e32 v80, v79, v79
	v_fmac_f32_e32 v69, v70, v70
	v_fmac_f32_e32 v80, v78, v78
	v_add_f32_e32 v69, v69, v80
	v_add_f32_e32 v68, v68, v69
	v_add_f32_e32 v80, v85, v68
	v_cvt_pk_bf16_f32 v68, v72, v73
	v_cvt_pk_bf16_f32 v69, v74, v75
	v_cvt_pk_bf16_f32 v70, v70, v71
	v_cvt_pk_bf16_f32 v71, v78, v79
	global_store_dwordx4 v[76:77], v[68:71], off offset:256
	s_nop 1
	v_mov_b32_e32 v68, v80
	s_nop 1
	v_permlane16_swap_b32_e32 v80, v68
	s_nop 0
	v_add_f32_e32 v68, v80, v68
	v_mov_b32_e32 v69, v68
	s_nop 1
	v_permlane32_swap_b32_e32 v68, v69
	v_add_f32_e32 v70, v68, v69
	s_and_saveexec_b64 s[2:3], s[40:41]
	s_cbranch_execz .LBB0_939
	s_nop 0
	v_floor_f32_e32 v72, v70
	v_sub_f32_e32 v70, v70, v72
	v_mul_f32_e32 v70, 0x4f800000, v70
	v_cvt_u32_f32_e32 v71, v72
	v_cvt_u32_f32_e32 v70, v70
	v_lshl_add_u64 v[68:69], v[186:187], 3, s[4:5]
	global_atomic_add_x2 v[68:69], v[70:71], off
.LBB0_939:
	s_or_b64 exec, exec, s[2:3]
	v_add_u32_e32 v102, 0x80, v182
	v_ashrrev_i32_e32 v103, 31, v102
	v_lshlrev_b64 v[110:111], 12, v[102:103]
	v_add_u32_e32 v100, 0x90, v182
	s_waitcnt lgkmcnt(0)
	v_lshl_add_u64 v[68:69], v[184:185], 0, v[110:111]
	v_ashrrev_i32_e32 v101, 31, v100
	global_load_dwordx4 v[106:109], v[68:69], off
	global_load_dwordx4 v[92:95], v[68:69], off offset:256
	v_lshlrev_b64 v[68:69], 12, v[100:101]
	v_add_u32_e32 v98, 0xa0, v182
	v_lshl_add_u64 v[68:69], v[184:185], 0, v[68:69]
	v_ashrrev_i32_e32 v99, 31, v98
	global_load_dwordx4 v[88:91], v[68:69], off
	global_load_dwordx4 v[84:87], v[68:69], off offset:256
	v_lshlrev_b64 v[68:69], 12, v[98:99]
	v_add_u32_e32 v96, 0xb0, v182
	v_lshl_add_u64 v[68:69], v[184:185], 0, v[68:69]
	v_ashrrev_i32_e32 v97, 31, v96
	global_load_dwordx4 v[80:83], v[68:69], off
	global_load_dwordx4 v[76:79], v[68:69], off offset:256
	v_lshlrev_b64 v[68:69], 12, v[96:97]
	v_lshl_add_u64 v[68:69], v[184:185], 0, v[68:69]
	global_load_dwordx4 v[72:75], v[68:69], off
	s_nop 0
	global_load_dwordx4 v[68:71], v[68:69], off offset:256
	s_nop 0
	v_mov_b32_e32 v113, v2
	s_waitcnt vmcnt(0)
	v_mov_b32_e32 v104, v244
	s_nop 0
	s_nop 0
	s_nop 0
	s_nop 1
	s_nop 1
	s_nop 0
	v_lshlrev_b32_e32 v112, 16, v106
	v_and_b32_e32 v113, 0xffff0000, v106
	v_lshlrev_b32_e32 v106, 16, v107
	v_and_b32_e32 v107, 0xffff0000, v107
	v_lshlrev_b32_e32 v114, 16, v108
	v_and_b32_e32 v115, 0xffff0000, v108
	v_lshlrev_b32_e32 v108, 16, v109
	v_and_b32_e32 v109, 0xffff0000, v109
	v_pk_fma_f32 v[66:67], v[66:67], v[104:105], v[106:107] op_sel_hi:[1,0,1]
	v_pk_fma_f32 v[64:65], v[64:65], v[104:105], v[112:113] op_sel_hi:[1,0,1]
	v_pk_fma_f32 v[106:107], v[62:63], v[104:105], v[108:109] op_sel_hi:[1,0,1]
	v_mul_f32_e32 v62, v65, v65
	v_mul_f32_e32 v63, v67, v67
	v_pk_fma_f32 v[60:61], v[60:61], v[104:105], v[114:115] op_sel_hi:[1,0,1]
	v_fmac_f32_e32 v62, v64, v64
	v_fmac_f32_e32 v63, v66, v66
	v_add_f32_e32 v62, v62, v63
	v_mul_f32_e32 v63, v61, v61
	v_mul_f32_e32 v105, v107, v107
	v_fmac_f32_e32 v63, v60, v60
	v_fmac_f32_e32 v105, v106, v106
	v_add_f32_e32 v63, v63, v105
	v_add_f32_e32 v105, v62, v63
	v_cvt_pk_bf16_f32 v62, v64, v65
	v_cvt_pk_bf16_f32 v64, v60, v61
	v_lshl_add_u64 v[60:61], s[64:65], 0, v[110:111]
	v_cvt_pk_bf16_f32 v63, v66, v67
	v_cvt_pk_bf16_f32 v65, v106, v107
	v_lshl_add_u64 v[60:61], v[0:1], 1, v[60:61]
	global_store_dwordx4 v[60:61], v[62:65], off
	v_lshlrev_b32_e32 v66, 16, v94
	v_and_b32_e32 v67, 0xffff0000, v94
	v_lshlrev_b32_e32 v62, 16, v92
	v_and_b32_e32 v63, 0xffff0000, v92
	v_lshlrev_b32_e32 v64, 16, v93
	v_and_b32_e32 v65, 0xffff0000, v93
	v_lshlrev_b32_e32 v92, 16, v95
	v_and_b32_e32 v93, 0xffff0000, v95
	v_pk_fma_f32 v[58:59], v[58:59], v[104:105], v[64:65] op_sel_hi:[1,0,1]
	v_pk_fma_f32 v[56:57], v[56:57], v[104:105], v[62:63] op_sel_hi:[1,0,1]
	v_pk_fma_f32 v[62:63], v[54:55], v[104:105], v[92:93] op_sel_hi:[1,0,1]
	v_pk_fma_f32 v[54:55], v[52:53], v[104:105], v[66:67] op_sel_hi:[1,0,1]
	v_mul_f32_e32 v52, v57, v57
	v_mul_f32_e32 v53, v59, v59
	v_fmac_f32_e32 v52, v56, v56
	v_fmac_f32_e32 v53, v58, v58
	v_add_f32_e32 v52, v52, v53
	v_mul_f32_e32 v53, v55, v55
	v_mul_f32_e32 v64, v63, v63
	v_fmac_f32_e32 v53, v54, v54
	v_fmac_f32_e32 v64, v62, v62
	v_add_f32_e32 v53, v53, v64
	v_add_f32_e32 v52, v52, v53
	v_add_f32_e32 v64, v105, v52
	v_cvt_pk_bf16_f32 v52, v56, v57
	v_cvt_pk_bf16_f32 v53, v58, v59
	v_cvt_pk_bf16_f32 v54, v54, v55
	v_cvt_pk_bf16_f32 v55, v62, v63
	global_store_dwordx4 v[60:61], v[52:55], off offset:256
	s_nop 1
	v_mov_b32_e32 v52, v64
	s_nop 1
	v_permlane16_swap_b32_e32 v64, v52
	s_nop 0
	v_add_f32_e32 v52, v64, v52
	v_mov_b32_e32 v53, v52
	s_nop 1
	v_permlane32_swap_b32_e32 v52, v53
	v_add_f32_e32 v54, v52, v53
	s_and_saveexec_b64 s[2:3], s[40:41]
	s_cbranch_execz .LBB0_941
; __device__ __forceinline__ void ss_add(ss_t* p, float sq) { const float fl = floorf(sq); const unsigned hi = (unsigned)fl, lo = (unsigned)((sq - fl) * 4294967296.0f); atomicAdd(p, ((ss_t)hi << 32) | (ss_t)lo); }
; __device__ __forceinline__ float ss_get(const ss_t* p) { const ss_t v = *p; return (float)(unsigned)(v >> 32) + (float)(unsigned)v * 2.3283064365386963e-10f; }
; __device__ __forceinline__ unsigned pkbf(float lo, float hi) { typedef float f2_t __attribute__((ext_vector_type(2))); typedef __bf16 b2_t __attribute__((ext_vector_type(2))); f2_t v = {lo, hi}; b2_t b = __builtin_convertvector(v, b2_t); return __builtin_bit_cast(unsigned, b); }
;     __device__ __forceinline__ void operator()(const f32x4 (&acc)[2][2][4][2], const Unit& u, int wr, int wc, int fr, int fq) const {
;     ...
;             for (int m = 0; m < 4; ++m) { const int row = row0 + ai * HALF + m * 16; const size_t off = (size_t)row * ldc + col0;
;                 float rs = 1.0f; if (KS) rs = 1.0f / sqrtf(ss_get(ssb + row) * (1.0f / 1024.f) + 1e-6f);
;                 float sq = 0.f;
; #pragma unroll
;                 for (int bj = 0; bj < 2; ++bj) { const u32x4 r = res[m][bj];
;                     const f32x4 x0 = (f32x4){__uint_as_float(r.x << 16), __uint_as_float(r.x & 0xffff0000u), __uint_as_float(r.y << 16), __uint_as_float(r.y & 0xffff0000u)};
;                     const f32x4 x1 = (f32x4){__uint_as_float(r.z << 16), __uint_as_float(r.z & 0xffff0000u), __uint_as_float(r.w << 16), __uint_as_float(r.w & 0xffff0000u)};
;                     const f32x4 v0 = x0 + acc[ai][bj][m][0] * rs, v1 = x1 + acc[ai][bj][m][1] * rs;
;                     if (OUT) { *(f32x4*)(OUT + off + bj * HALF) = v0; *(f32x4*)(OUT + off + bj * HALF + 4) = v1; }
;                     else { sq += ((v0[0] * v0[0] + v0[1] * v0[1]) + (v0[2] * v0[2] + v0[3] * v0[3])) + ((v1[0] * v1[0] + v1[1] * v1[1]) + (v1[2] * v1[2] + v1[3] * v1[3]));
;                         u32x4 w; w.x = pkbf(v0[0], v0[1]); w.y = pkbf(v0[2], v0[3]); w.z = pkbf(v1[0], v1[1]); w.w = pkbf(v1[2], v1[3]); *(u32x4*)(XB + off + bj * HALF) = w; } }
;                 if (!OUT) { sq += __shfl_xor(sq, 16); sq += __shfl_xor(sq, 32); if (fq == 0) ss_add(ssq_out + row, sq); } }
	s_nop 0
	v_floor_f32_e32 v56, v54
	v_sub_f32_e32 v54, v54, v56
	v_mul_f32_e32 v54, 0x4f800000, v54
	v_cvt_u32_f32_e32 v55, v56
	v_cvt_u32_f32_e32 v54, v54
	v_lshl_add_u64 v[52:53], v[102:103], 3, s[4:5]
	global_atomic_add_x2 v[52:53], v[54:55], off
.LBB0_941:
	s_or_b64 exec, exec, s[2:3]
	s_waitcnt lgkmcnt(0)
	s_nop 0
	v_mov_b32_e32 v57, v2
	v_lshlrev_b32_e32 v62, 16, v91
	v_and_b32_e32 v63, 0xffff0000, v91
	v_lshlrev_b32_e32 v60, 16, v90
	v_and_b32_e32 v61, 0xffff0000, v90
	v_lshlrev_b64 v[54:55], 11, v[100:101]
	v_mov_b32_e32 v52, v245
	s_nop 0
	s_nop 0
	s_nop 0
	s_nop 1
	s_nop 1
	s_nop 0
	v_lshlrev_b32_e32 v56, 16, v88
	v_and_b32_e32 v57, 0xffff0000, v88
	v_lshlrev_b32_e32 v58, 16, v89
	v_and_b32_e32 v59, 0xffff0000, v89
	v_pk_fma_f32 v[50:51], v[50:51], v[52:53], v[58:59] op_sel_hi:[1,0,1]
	v_pk_fma_f32 v[48:49], v[48:49], v[52:53], v[56:57] op_sel_hi:[1,0,1]
	v_pk_fma_f32 v[56:57], v[46:47], v[52:53], v[62:63] op_sel_hi:[1,0,1]
	v_mul_f32_e32 v46, v49, v49
	v_mul_f32_e32 v47, v51, v51
	v_pk_fma_f32 v[44:45], v[44:45], v[52:53], v[60:61] op_sel_hi:[1,0,1]
	v_fmac_f32_e32 v46, v48, v48
	v_fmac_f32_e32 v47, v50, v50
	v_add_f32_e32 v46, v46, v47
	v_mul_f32_e32 v47, v45, v45
	v_mul_f32_e32 v53, v57, v57
	v_fmac_f32_e32 v47, v44, v44
	v_fmac_f32_e32 v53, v56, v56
	v_add_f32_e32 v47, v47, v53
	v_add_f32_e32 v53, v46, v47
	v_cvt_pk_bf16_f32 v46, v48, v49
	v_cvt_pk_bf16_f32 v48, v44, v45
	v_lshl_add_u64 v[44:45], v[54:55], 1, s[64:65]
	v_cvt_pk_bf16_f32 v47, v50, v51
	v_cvt_pk_bf16_f32 v49, v56, v57
	v_lshl_add_u64 v[44:45], v[0:1], 1, v[44:45]
	global_store_dwordx4 v[44:45], v[46:49], off
	v_lshlrev_b32_e32 v50, 16, v86
	v_and_b32_e32 v51, 0xffff0000, v86
	v_lshlrev_b32_e32 v46, 16, v84
	v_and_b32_e32 v47, 0xffff0000, v84
	v_lshlrev_b32_e32 v48, 16, v85
	v_and_b32_e32 v49, 0xffff0000, v85
	v_lshlrev_b32_e32 v54, 16, v87
	v_and_b32_e32 v55, 0xffff0000, v87
	v_pk_fma_f32 v[42:43], v[42:43], v[52:53], v[48:49] op_sel_hi:[1,0,1]
	v_pk_fma_f32 v[40:41], v[40:41], v[52:53], v[46:47] op_sel_hi:[1,0,1]
	v_pk_fma_f32 v[46:47], v[38:39], v[52:53], v[54:55] op_sel_hi:[1,0,1]
	v_pk_fma_f32 v[38:39], v[36:37], v[52:53], v[50:51] op_sel_hi:[1,0,1]
	v_mul_f32_e32 v36, v41, v41
	v_mul_f32_e32 v37, v43, v43
	v_fmac_f32_e32 v36, v40, v40
	v_fmac_f32_e32 v37, v42, v42
	v_add_f32_e32 v36, v36, v37
	v_mul_f32_e32 v37, v39, v39
	v_mul_f32_e32 v48, v47, v47
	v_fmac_f32_e32 v37, v38, v38
	v_fmac_f32_e32 v48, v46, v46
	v_add_f32_e32 v37, v37, v48
	v_add_f32_e32 v36, v36, v37
	v_add_f32_e32 v48, v53, v36
	v_cvt_pk_bf16_f32 v36, v40, v41
	v_cvt_pk_bf16_f32 v37, v42, v43
	v_cvt_pk_bf16_f32 v38, v38, v39
	v_cvt_pk_bf16_f32 v39, v46, v47
	global_store_dwordx4 v[44:45], v[36:39], off offset:256
	s_nop 1
	v_mov_b32_e32 v36, v48
	s_nop 1
	v_permlane16_swap_b32_e32 v48, v36
	s_nop 0
	v_add_f32_e32 v36, v48, v36
	v_mov_b32_e32 v37, v36
	s_nop 1
	v_permlane32_swap_b32_e32 v36, v37
	v_add_f32_e32 v38, v36, v37
	s_and_saveexec_b64 s[2:3], s[40:41]
	s_cbranch_execz .LBB0_943
	s_nop 0
	v_floor_f32_e32 v40, v38
	v_sub_f32_e32 v38, v38, v40
	v_mul_f32_e32 v38, 0x4f800000, v38
	v_cvt_u32_f32_e32 v39, v40
	v_cvt_u32_f32_e32 v38, v38
	v_lshl_add_u64 v[36:37], v[100:101], 3, s[4:5]
	global_atomic_add_x2 v[36:37], v[38:39], off
; __device__ __forceinline__ void ss_add(ss_t* p, float sq) { const float fl = floorf(sq); const unsigned hi = (unsigned)fl, lo = (unsigned)((sq - fl) * 4294967296.0f); atomicAdd(p, ((ss_t)hi << 32) | (ss_t)lo); }
; __device__ __forceinline__ float ss_get(const ss_t* p) { const ss_t v = *p; return (float)(unsigned)(v >> 32) + (float)(unsigned)v * 2.3283064365386963e-10f; }
; __device__ __forceinline__ unsigned pkbf(float lo, float hi) { typedef float f2_t __attribute__((ext_vector_type(2))); typedef __bf16 b2_t __attribute__((ext_vector_type(2))); f2_t v = {lo, hi}; b2_t b = __builtin_convertvector(v, b2_t); return __builtin_bit_cast(unsigned, b); }
;     __device__ __forceinline__ void operator()(const f32x4 (&acc)[2][2][4][2], const Unit& u, int wr, int wc, int fr, int fq) const {
;     ...
;             for (int m = 0; m < 4; ++m) { const int row = row0 + ai * HALF + m * 16; const size_t off = (size_t)row * ldc + col0;
;                 float rs = 1.0f; if (KS) rs = 1.0f / sqrtf(ss_get(ssb + row) * (1.0f / 1024.f) + 1e-6f);
;                 float sq = 0.f;
; #pragma unroll
;                 for (int bj = 0; bj < 2; ++bj) { const u32x4 r = res[m][bj];
;                     const f32x4 x0 = (f32x4){__uint_as_float(r.x << 16), __uint_as_float(r.x & 0xffff0000u), __uint_as_float(r.y << 16), __uint_as_float(r.y & 0xffff0000u)};
;                     const f32x4 x1 = (f32x4){__uint_as_float(r.z << 16), __uint_as_float(r.z & 0xffff0000u), __uint_as_float(r.w << 16), __uint_as_float(r.w & 0xffff0000u)};
;                     const f32x4 v0 = x0 + acc[ai][bj][m][0] * rs, v1 = x1 + acc[ai][bj][m][1] * rs;
;                     if (OUT) { *(f32x4*)(OUT + off + bj * HALF) = v0; *(f32x4*)(OUT + off + bj * HALF + 4) = v1; }
;                     else { sq += ((v0[0] * v0[0] + v0[1] * v0[1]) + (v0[2] * v0[2] + v0[3] * v0[3])) + ((v1[0] * v1[0] + v1[1] * v1[1]) + (v1[2] * v1[2] + v1[3] * v1[3]));
;                         u32x4 w; w.x = pkbf(v0[0], v0[1]); w.y = pkbf(v0[2], v0[3]); w.z = pkbf(v1[0], v1[1]); w.w = pkbf(v1[2], v1[3]); *(u32x4*)(XB + off + bj * HALF) = w; } }
;                 if (!OUT) { sq += __shfl_xor(sq, 16); sq += __shfl_xor(sq, 32); if (fq == 0) ss_add(ssq_out + row, sq); } }
.LBB0_943:
	s_or_b64 exec, exec, s[2:3]
	s_waitcnt lgkmcnt(0)
	s_nop 0
	v_mov_b32_e32 v41, v2
	v_lshlrev_b32_e32 v46, 16, v83
	v_and_b32_e32 v47, 0xffff0000, v83
	v_lshlrev_b32_e32 v44, 16, v82
	v_and_b32_e32 v45, 0xffff0000, v82
	v_lshlrev_b64 v[38:39], 11, v[98:99]
	v_mov_b32_e32 v36, v246
	s_nop 0
	s_nop 0
	s_nop 0
	s_nop 1
	s_nop 1
	s_nop 0
	v_lshlrev_b32_e32 v40, 16, v80
	v_and_b32_e32 v41, 0xffff0000, v80
	v_lshlrev_b32_e32 v42, 16, v81
	v_and_b32_e32 v43, 0xffff0000, v81
	v_pk_fma_f32 v[34:35], v[34:35], v[36:37], v[42:43] op_sel_hi:[1,0,1]
	v_pk_fma_f32 v[32:33], v[32:33], v[36:37], v[40:41] op_sel_hi:[1,0,1]
	v_pk_fma_f32 v[40:41], v[30:31], v[36:37], v[46:47] op_sel_hi:[1,0,1]
	v_mul_f32_e32 v30, v33, v33
	v_mul_f32_e32 v31, v35, v35
	v_pk_fma_f32 v[28:29], v[28:29], v[36:37], v[44:45] op_sel_hi:[1,0,1]
	v_fmac_f32_e32 v30, v32, v32
	v_fmac_f32_e32 v31, v34, v34
	v_add_f32_e32 v30, v30, v31
	v_mul_f32_e32 v31, v29, v29
	v_mul_f32_e32 v37, v41, v41
	v_fmac_f32_e32 v31, v28, v28
	v_fmac_f32_e32 v37, v40, v40
	v_add_f32_e32 v31, v31, v37
	v_add_f32_e32 v37, v30, v31
	v_cvt_pk_bf16_f32 v30, v32, v33
	v_cvt_pk_bf16_f32 v32, v28, v29
	v_lshl_add_u64 v[28:29], v[38:39], 1, s[64:65]
	v_cvt_pk_bf16_f32 v31, v34, v35
	v_cvt_pk_bf16_f32 v33, v40, v41
	v_lshl_add_u64 v[28:29], v[0:1], 1, v[28:29]
	global_store_dwordx4 v[28:29], v[30:33], off
	v_lshlrev_b32_e32 v34, 16, v78
	v_and_b32_e32 v35, 0xffff0000, v78
	v_lshlrev_b32_e32 v30, 16, v76
	v_and_b32_e32 v31, 0xffff0000, v76
	v_lshlrev_b32_e32 v32, 16, v77
	v_and_b32_e32 v33, 0xffff0000, v77
	v_lshlrev_b32_e32 v38, 16, v79
	v_and_b32_e32 v39, 0xffff0000, v79
	v_pk_fma_f32 v[26:27], v[26:27], v[36:37], v[32:33] op_sel_hi:[1,0,1]
	v_pk_fma_f32 v[24:25], v[24:25], v[36:37], v[30:31] op_sel_hi:[1,0,1]
	v_pk_fma_f32 v[30:31], v[22:23], v[36:37], v[38:39] op_sel_hi:[1,0,1]
	v_pk_fma_f32 v[22:23], v[20:21], v[36:37], v[34:35] op_sel_hi:[1,0,1]
	v_mul_f32_e32 v20, v25, v25
	v_mul_f32_e32 v21, v27, v27
	v_fmac_f32_e32 v20, v24, v24
	v_fmac_f32_e32 v21, v26, v26
	v_add_f32_e32 v20, v20, v21
	v_mul_f32_e32 v21, v23, v23
	v_mul_f32_e32 v32, v31, v31
	v_fmac_f32_e32 v21, v22, v22
	v_fmac_f32_e32 v32, v30, v30
	v_add_f32_e32 v21, v21, v32
	v_add_f32_e32 v20, v20, v21
	v_add_f32_e32 v32, v37, v20
	v_cvt_pk_bf16_f32 v20, v24, v25
	v_cvt_pk_bf16_f32 v21, v26, v27
	v_cvt_pk_bf16_f32 v22, v22, v23
	v_cvt_pk_bf16_f32 v23, v30, v31
	global_store_dwordx4 v[28:29], v[20:23], off offset:256
	s_nop 1
	v_mov_b32_e32 v20, v32
	s_nop 1
	v_permlane16_swap_b32_e32 v32, v20
	s_nop 0
	v_add_f32_e32 v20, v32, v20
	v_mov_b32_e32 v21, v20
	s_nop 1
	v_permlane32_swap_b32_e32 v20, v21
	v_add_f32_e32 v22, v20, v21
	s_and_saveexec_b64 s[2:3], s[40:41]
	s_cbranch_execz .LBB0_945
	s_nop 0
	v_floor_f32_e32 v24, v22
	v_sub_f32_e32 v22, v22, v24
	v_mul_f32_e32 v22, 0x4f800000, v22
	v_cvt_u32_f32_e32 v23, v24
	v_cvt_u32_f32_e32 v22, v22
	v_lshl_add_u64 v[20:21], v[98:99], 3, s[4:5]
	global_atomic_add_x2 v[20:21], v[22:23], off
.LBB0_945:
	s_or_b64 exec, exec, s[2:3]
	s_waitcnt lgkmcnt(0)
	s_nop 0
	v_mov_b32_e32 v25, v2
	v_lshlrev_b32_e32 v28, 16, v74
	v_and_b32_e32 v29, 0xffff0000, v74
	v_lshlrev_b32_e32 v30, 16, v75
	v_and_b32_e32 v31, 0xffff0000, v75
	v_lshlrev_b64 v[22:23], 11, v[96:97]
	v_mov_b32_e32 v20, v252
	s_nop 0
	s_nop 0
	s_nop 0
	s_nop 1
	s_nop 1
	s_nop 0
	v_lshlrev_b32_e32 v24, 16, v72
	v_and_b32_e32 v25, 0xffff0000, v72
	v_lshlrev_b32_e32 v26, 16, v73
	v_and_b32_e32 v27, 0xffff0000, v73
	v_pk_fma_f32 v[18:19], v[18:19], v[20:21], v[26:27] op_sel_hi:[1,0,1]
	v_pk_fma_f32 v[16:17], v[16:17], v[20:21], v[24:25] op_sel_hi:[1,0,1]
	v_pk_fma_f32 v[24:25], v[14:15], v[20:21], v[30:31] op_sel_hi:[1,0,1]
	v_pk_fma_f32 v[14:15], v[12:13], v[20:21], v[28:29] op_sel_hi:[1,0,1]
	v_mul_f32_e32 v12, v17, v17
	v_mul_f32_e32 v13, v19, v19
	v_fmac_f32_e32 v12, v16, v16
	v_fmac_f32_e32 v13, v18, v18
	v_add_f32_e32 v12, v12, v13
	v_mul_f32_e32 v13, v15, v15
	v_mul_f32_e32 v21, v25, v25
	v_fmac_f32_e32 v13, v14, v14
	v_fmac_f32_e32 v21, v24, v24
	v_add_f32_e32 v13, v13, v21
	v_add_f32_e32 v21, v12, v13
	v_cvt_pk_bf16_f32 v12, v16, v17
	v_lshl_add_u64 v[16:17], v[22:23], 1, s[64:65]
	v_cvt_pk_bf16_f32 v13, v18, v19
	v_cvt_pk_bf16_f32 v14, v14, v15
	v_cvt_pk_bf16_f32 v15, v24, v25
	v_lshl_add_u64 v[0:1], v[0:1], 1, v[16:17]
	global_store_dwordx4 v[0:1], v[12:15], off
	v_lshlrev_b32_e32 v16, 16, v70
	v_and_b32_e32 v17, 0xffff0000, v70
	v_lshlrev_b32_e32 v12, 16, v68
	v_and_b32_e32 v13, 0xffff0000, v68
	v_lshlrev_b32_e32 v14, 16, v69
	v_and_b32_e32 v15, 0xffff0000, v69
	v_lshlrev_b32_e32 v18, 16, v71
	v_and_b32_e32 v19, 0xffff0000, v71
	v_pk_fma_f32 v[10:11], v[10:11], v[20:21], v[14:15] op_sel_hi:[1,0,1]
	v_pk_fma_f32 v[8:9], v[8:9], v[20:21], v[12:13] op_sel_hi:[1,0,1]
	v_pk_fma_f32 v[12:13], v[6:7], v[20:21], v[18:19] op_sel_hi:[1,0,1]
	v_pk_fma_f32 v[6:7], v[4:5], v[20:21], v[16:17] op_sel_hi:[1,0,1]
	v_mul_f32_e32 v4, v9, v9
	v_mul_f32_e32 v5, v11, v11
	v_fmac_f32_e32 v4, v8, v8
	v_fmac_f32_e32 v5, v10, v10
	v_add_f32_e32 v4, v4, v5
	v_mul_f32_e32 v5, v7, v7
	v_mul_f32_e32 v14, v13, v13
	v_fmac_f32_e32 v5, v6, v6
	v_fmac_f32_e32 v14, v12, v12
	v_add_f32_e32 v5, v5, v14
	v_add_f32_e32 v4, v4, v5
	v_add_f32_e32 v14, v21, v4
	v_cvt_pk_bf16_f32 v4, v8, v9
	v_cvt_pk_bf16_f32 v5, v10, v11
	v_cvt_pk_bf16_f32 v6, v6, v7
	v_cvt_pk_bf16_f32 v7, v12, v13
	global_store_dwordx4 v[0:1], v[4:7], off offset:256
	v_mov_b32_e32 v0, v14
	s_nop 1
	v_permlane16_swap_b32_e32 v14, v0
	s_nop 0
	v_add_f32_e32 v0, v14, v0
	v_mov_b32_e32 v1, v0
	s_nop 1
	v_permlane32_swap_b32_e32 v0, v1
	v_add_f32_e32 v3, v0, v1
	s_and_saveexec_b64 s[2:3], s[40:41]
	s_cbranch_execz .LBB0_947
	s_nop 0
	v_floor_f32_e32 v4, v3
	v_sub_f32_e32 v3, v3, v4
	v_mul_f32_e32 v3, 0x4f800000, v3
	v_cvt_u32_f32_e32 v5, v4
	v_cvt_u32_f32_e32 v4, v3
	v_lshl_add_u64 v[0:1], v[96:97], 3, s[4:5]
	global_atomic_add_x2 v[0:1], v[4:5], off

; __device__ __forceinline__ void ss_add(ss_t* p, float sq) { const float fl = floorf(sq); const unsigned hi = (unsigned)fl, lo = (unsigned)((sq - fl) * 4294967296.0f); atomicAdd(p, ((ss_t)hi << 32) | (ss_t)lo); }
;     __device__ __forceinline__ void operator()(const f32x4 (&acc)[2][2][4][2], const Unit& u, int wr, int wc, int fr, int fq) const {
;     ...
;                 if (!OUT) { sq += __shfl_xor(sq, 16); sq += __shfl_xor(sq, 32); if (fq == 0) ss_add(ssq_out + row, sq); } }
.LBB0_1289:
	v_readlane_b32 s68, v250, 1
	v_cndmask_b32_e64 v116, 0, 1, s[14:15]
	v_readlane_b32 s70, v250, 3
	v_readlane_b32 s71, v250, 4
	v_cmp_ne_u32_e64 s[2:3], 1, v116
	s_andn2_b64 vcc, exec, s[14:15]
	s_mov_b64 s[46:47], s[70:71]
	v_readlane_b32 s69, v250, 2
	s_cbranch_vccnz .LBB0_1293
	v_and_b32_e32 v117, 64, v208
	v_xor_b32_e32 v116, 16, v208
	v_add_u32_e32 v117, 64, v117
	v_cmp_lt_i32_e32 vcc, v116, v117
	v_xor_b32_e32 v118, 32, v208
	s_nop 0
	v_cndmask_b32_e32 v116, v208, v116, vcc
	v_lshlrev_b32_e32 v116, 2, v116
	v_mov_b32_e32 v116, v215
	s_nop 1
	v_permlane16_swap_b32_e32 v215, v116
	v_cmp_lt_i32_e32 vcc, v118, v117
	s_nop 0
	v_add_f32_e32 v116, v215, v116
	v_cndmask_b32_e32 v117, v208, v118, vcc
	v_lshlrev_b32_e32 v117, 2, v117
	v_mov_b32_e32 v117, v116
	s_nop 1
	v_permlane32_swap_b32_e32 v116, v117
	v_add_f32_e32 v116, v116, v117
	s_and_saveexec_b64 s[46:47], s[36:37]
	s_cbranch_execz .LBB0_1292
	s_nop 0
	v_floor_f32_e32 v118, v116
	v_sub_f32_e32 v116, v116, v118
	v_mul_f32_e32 v116, 0x4f800000, v116
	v_cvt_u32_f32_e32 v117, v118
	v_cvt_u32_f32_e32 v116, v116
	v_lshl_add_u64 v[118:119], v[182:183], 3, s[8:9]
	global_atomic_add_x2 v[118:119], v[116:117], off

; __device__ __forceinline__ void ss_add(ss_t* p, float sq) { const float fl = floorf(sq); const unsigned hi = (unsigned)fl, lo = (unsigned)((sq - fl) * 4294967296.0f); atomicAdd(p, ((ss_t)hi << 32) | (ss_t)lo); }
;     __device__ __forceinline__ void operator()(const f32x4 (&acc)[2][2][4][2], const Unit& u, int wr, int wc, int fr, int fq) const {
;     ...
;                 if (!OUT) { sq += __shfl_xor(sq, 16); sq += __shfl_xor(sq, 32); if (fq == 0) ss_add(ssq_out + row, sq); } }
.LBB0_1300:
	v_readlane_b32 s68, v250, 1
	v_readlane_b32 s70, v250, 3
	v_readlane_b32 s71, v250, 4
	s_and_b64 vcc, exec, s[2:3]
	s_mov_b64 s[46:47], s[70:71]
	v_readlane_b32 s69, v250, 2
	s_cbranch_vccnz .LBB0_1304
	v_and_b32_e32 v101, 64, v208
	v_xor_b32_e32 v100, 16, v208
	v_add_u32_e32 v101, 64, v101
	v_cmp_lt_i32_e32 vcc, v100, v101
	v_xor_b32_e32 v102, 32, v208
	s_nop 0
	v_cndmask_b32_e32 v100, v208, v100, vcc
	v_lshlrev_b32_e32 v100, 2, v100
	v_mov_b32_e32 v100, v118
	s_nop 1
	v_permlane16_swap_b32_e32 v118, v100
	v_cmp_lt_i32_e32 vcc, v102, v101
	s_nop 0
	v_add_f32_e32 v100, v118, v100
	v_cndmask_b32_e32 v101, v208, v102, vcc
	v_lshlrev_b32_e32 v101, 2, v101
	v_mov_b32_e32 v101, v100
	s_nop 1
	v_permlane32_swap_b32_e32 v100, v101
	v_add_f32_e32 v100, v100, v101
	s_and_saveexec_b64 s[46:47], s[36:37]
	s_cbranch_execz .LBB0_1303
	s_nop 0
	v_floor_f32_e32 v102, v100
	v_sub_f32_e32 v100, v100, v102
	v_mul_f32_e32 v100, 0x4f800000, v100
	v_cvt_u32_f32_e32 v101, v102
	v_cvt_u32_f32_e32 v100, v100
	v_lshl_add_u64 v[102:103], v[182:183], 3, s[8:9]
	global_atomic_add_x2 v[102:103], v[100:101], off offset:128

; __device__ __forceinline__ void ss_add(ss_t* p, float sq) { const float fl = floorf(sq); const unsigned hi = (unsigned)fl, lo = (unsigned)((sq - fl) * 4294967296.0f); atomicAdd(p, ((ss_t)hi << 32) | (ss_t)lo); }
;     __device__ __forceinline__ void operator()(const f32x4 (&acc)[2][2][4][2], const Unit& u, int wr, int wc, int fr, int fq) const {
;     ...
;                 if (!OUT) { sq += __shfl_xor(sq, 16); sq += __shfl_xor(sq, 32); if (fq == 0) ss_add(ssq_out + row, sq); } }
.LBB0_1311:
	v_readlane_b32 s68, v250, 1
	v_readlane_b32 s70, v250, 3
	v_readlane_b32 s71, v250, 4
	s_and_b64 vcc, exec, s[2:3]
	s_mov_b64 s[46:47], s[70:71]
	v_readlane_b32 s69, v250, 2
	s_cbranch_vccnz .LBB0_1315
	v_and_b32_e32 v85, 64, v208
	v_xor_b32_e32 v84, 16, v208
	v_add_u32_e32 v85, 64, v85
	v_cmp_lt_i32_e32 vcc, v84, v85
	v_xor_b32_e32 v86, 32, v208
	s_nop 0
	v_cndmask_b32_e32 v84, v208, v84, vcc
	v_lshlrev_b32_e32 v84, 2, v84
	v_mov_b32_e32 v84, v102
	s_nop 1
	v_permlane16_swap_b32_e32 v102, v84
	v_cmp_lt_i32_e32 vcc, v86, v85
	s_nop 0
	v_add_f32_e32 v84, v102, v84
	v_cndmask_b32_e32 v85, v208, v86, vcc
	v_lshlrev_b32_e32 v85, 2, v85
	v_mov_b32_e32 v85, v84
	s_nop 1
	v_permlane32_swap_b32_e32 v84, v85
	v_add_f32_e32 v84, v84, v85
	s_and_saveexec_b64 s[46:47], s[36:37]
	s_cbranch_execz .LBB0_1314
	s_nop 0
	v_floor_f32_e32 v86, v84
	v_sub_f32_e32 v84, v84, v86
	v_mul_f32_e32 v84, 0x4f800000, v84
	v_cvt_u32_f32_e32 v85, v86
	v_cvt_u32_f32_e32 v84, v84
	v_lshl_add_u64 v[86:87], v[182:183], 3, s[8:9]
	global_atomic_add_x2 v[86:87], v[84:85], off offset:256

; __device__ __forceinline__ void ss_add(ss_t* p, float sq) { const float fl = floorf(sq); const unsigned hi = (unsigned)fl, lo = (unsigned)((sq - fl) * 4294967296.0f); atomicAdd(p, ((ss_t)hi << 32) | (ss_t)lo); }
;     __device__ __forceinline__ void operator()(const f32x4 (&acc)[2][2][4][2], const Unit& u, int wr, int wc, int fr, int fq) const {
;     ...
;                 if (!OUT) { sq += __shfl_xor(sq, 16); sq += __shfl_xor(sq, 32); if (fq == 0) ss_add(ssq_out + row, sq); } }
.LBB0_1323:
	v_and_b32_e32 v69, 64, v208
	v_xor_b32_e32 v68, 16, v208
	v_add_u32_e32 v69, 64, v69
	v_cmp_lt_i32_e32 vcc, v68, v69
	v_xor_b32_e32 v70, 32, v208
	s_nop 0
	v_cndmask_b32_e32 v68, v208, v68, vcc
	v_lshlrev_b32_e32 v68, 2, v68
	v_mov_b32_e32 v68, v86
	s_nop 1
	v_permlane16_swap_b32_e32 v86, v68
	v_cmp_lt_i32_e32 vcc, v70, v69
	s_nop 0
	v_add_f32_e32 v68, v86, v68
	v_cndmask_b32_e32 v69, v208, v70, vcc
	v_lshlrev_b32_e32 v69, 2, v69
	v_mov_b32_e32 v69, v68
	s_nop 1
	v_permlane32_swap_b32_e32 v68, v69
	v_add_f32_e32 v68, v68, v69
	s_and_saveexec_b64 s[46:47], s[36:37]
	s_cbranch_execz .LBB0_1325
	s_nop 0
	v_floor_f32_e32 v70, v68
	v_sub_f32_e32 v68, v68, v70
	v_mul_f32_e32 v68, 0x4f800000, v68
	v_cvt_u32_f32_e32 v69, v70
	v_cvt_u32_f32_e32 v68, v68
	v_lshl_add_u64 v[70:71], v[182:183], 3, s[8:9]
	global_atomic_add_x2 v[70:71], v[68:69], off offset:384

; __device__ __forceinline__ void ss_add(ss_t* p, float sq) { const float fl = floorf(sq); const unsigned hi = (unsigned)fl, lo = (unsigned)((sq - fl) * 4294967296.0f); atomicAdd(p, ((ss_t)hi << 32) | (ss_t)lo); }
;     __device__ __forceinline__ void operator()(const f32x4 (&acc)[2][2][4][2], const Unit& u, int wr, int wc, int fr, int fq) const {
;     ...
;                 if (!OUT) { sq += __shfl_xor(sq, 16); sq += __shfl_xor(sq, 32); if (fq == 0) ss_add(ssq_out + row, sq); } }
.LBB0_1334:
	v_readlane_b32 s68, v250, 1
	v_readlane_b32 s70, v250, 3
	v_readlane_b32 s71, v250, 4
	s_and_b64 vcc, exec, s[2:3]
	s_mov_b64 s[46:47], s[70:71]
	v_readlane_b32 s69, v250, 2
	s_cbranch_vccnz .LBB0_1338
	v_and_b32_e32 v53, 64, v208
	v_xor_b32_e32 v52, 16, v208
	v_add_u32_e32 v53, 64, v53
	v_cmp_lt_i32_e32 vcc, v52, v53
	v_xor_b32_e32 v54, 32, v208
	s_nop 0
	v_cndmask_b32_e32 v52, v208, v52, vcc
	v_lshlrev_b32_e32 v52, 2, v52
	v_mov_b32_e32 v52, v112
	s_nop 1
	v_permlane16_swap_b32_e32 v112, v52
	v_cmp_lt_i32_e32 vcc, v54, v53
	s_nop 0
	v_add_f32_e32 v52, v112, v52
	v_cndmask_b32_e32 v53, v208, v54, vcc
	v_lshlrev_b32_e32 v53, 2, v53
	v_mov_b32_e32 v53, v52
	s_nop 1
	v_permlane32_swap_b32_e32 v52, v53
	v_add_f32_e32 v52, v52, v53
	s_and_saveexec_b64 s[46:47], s[36:37]
	s_cbranch_execz .LBB0_1337
	s_nop 0
	v_floor_f32_e32 v54, v52
	v_sub_f32_e32 v52, v52, v54
	v_mul_f32_e32 v52, 0x4f800000, v52
	v_cvt_u32_f32_e32 v53, v54
	v_cvt_u32_f32_e32 v52, v52
	v_lshl_add_u64 v[54:55], v[182:183], 3, s[8:9]
	global_atomic_add_x2 v[54:55], v[52:53], off offset:1024

; __device__ __forceinline__ void ss_add(ss_t* p, float sq) { const float fl = floorf(sq); const unsigned hi = (unsigned)fl, lo = (unsigned)((sq - fl) * 4294967296.0f); atomicAdd(p, ((ss_t)hi << 32) | (ss_t)lo); }
;     __device__ __forceinline__ void operator()(const f32x4 (&acc)[2][2][4][2], const Unit& u, int wr, int wc, int fr, int fq) const {
;     ...
;                 if (!OUT) { sq += __shfl_xor(sq, 16); sq += __shfl_xor(sq, 32); if (fq == 0) ss_add(ssq_out + row, sq); } }
.LBB0_1345:
	v_readlane_b32 s68, v250, 1
	v_readlane_b32 s70, v250, 3
	v_readlane_b32 s71, v250, 4
	s_and_b64 vcc, exec, s[2:3]
	s_mov_b64 s[46:47], s[70:71]
	v_readlane_b32 s69, v250, 2
	s_cbranch_vccnz .LBB0_1349
	v_and_b32_e32 v37, 64, v208
	v_xor_b32_e32 v36, 16, v208
	v_add_u32_e32 v37, 64, v37
	v_cmp_lt_i32_e32 vcc, v36, v37
	v_xor_b32_e32 v38, 32, v208
	s_nop 0
	v_cndmask_b32_e32 v36, v208, v36, vcc
	v_lshlrev_b32_e32 v36, 2, v36
	v_mov_b32_e32 v36, v54
	s_nop 1
	v_permlane16_swap_b32_e32 v54, v36
	v_cmp_lt_i32_e32 vcc, v38, v37
	s_nop 0
	v_add_f32_e32 v36, v54, v36
	v_cndmask_b32_e32 v37, v208, v38, vcc
	v_lshlrev_b32_e32 v37, 2, v37
	v_mov_b32_e32 v37, v36
	s_nop 1
	v_permlane32_swap_b32_e32 v36, v37
	v_add_f32_e32 v36, v36, v37
	s_and_saveexec_b64 s[46:47], s[36:37]
	s_cbranch_execz .LBB0_1348
	s_nop 0
	v_floor_f32_e32 v38, v36
	v_sub_f32_e32 v36, v36, v38
	v_mul_f32_e32 v36, 0x4f800000, v36
	v_cvt_u32_f32_e32 v37, v38
	v_cvt_u32_f32_e32 v36, v36
	v_lshl_add_u64 v[38:39], v[182:183], 3, s[8:9]
	global_atomic_add_x2 v[38:39], v[36:37], off offset:1152

; __device__ __forceinline__ void ss_add(ss_t* p, float sq) { const float fl = floorf(sq); const unsigned hi = (unsigned)fl, lo = (unsigned)((sq - fl) * 4294967296.0f); atomicAdd(p, ((ss_t)hi << 32) | (ss_t)lo); }
;     __device__ __forceinline__ void operator()(const f32x4 (&acc)[2][2][4][2], const Unit& u, int wr, int wc, int fr, int fq) const {
;     ...
;                 if (!OUT) { sq += __shfl_xor(sq, 16); sq += __shfl_xor(sq, 32); if (fq == 0) ss_add(ssq_out + row, sq); } }
.LBB0_1356:
	v_readlane_b32 s68, v250, 1
	v_readlane_b32 s70, v250, 3
	v_readlane_b32 s71, v250, 4
	s_and_b64 vcc, exec, s[2:3]
	s_mov_b64 s[46:47], s[70:71]
	v_readlane_b32 s69, v250, 2
	s_cbranch_vccnz .LBB0_1360
	v_and_b32_e32 v21, 64, v208
	v_xor_b32_e32 v20, 16, v208
	v_add_u32_e32 v21, 64, v21
	v_cmp_lt_i32_e32 vcc, v20, v21
	v_xor_b32_e32 v22, 32, v208
	s_nop 0
	v_cndmask_b32_e32 v20, v208, v20, vcc
	v_lshlrev_b32_e32 v20, 2, v20
	v_mov_b32_e32 v20, v38
	s_nop 1
	v_permlane16_swap_b32_e32 v38, v20
	v_cmp_lt_i32_e32 vcc, v22, v21
	s_nop 0
	v_add_f32_e32 v20, v38, v20
	v_cndmask_b32_e32 v21, v208, v22, vcc
	v_lshlrev_b32_e32 v21, 2, v21
	v_mov_b32_e32 v21, v20
	s_nop 1
	v_permlane32_swap_b32_e32 v20, v21
	v_add_f32_e32 v20, v20, v21
	s_and_saveexec_b64 s[46:47], s[36:37]
	s_cbranch_execz .LBB0_1359
	s_nop 0
	v_floor_f32_e32 v22, v20
	v_sub_f32_e32 v20, v20, v22
	v_mul_f32_e32 v20, 0x4f800000, v20
	v_cvt_u32_f32_e32 v21, v22
	v_cvt_u32_f32_e32 v20, v20
	v_lshl_add_u64 v[22:23], v[182:183], 3, s[8:9]
	global_atomic_add_x2 v[22:23], v[20:21], off offset:1280

; __device__ __forceinline__ void ss_add(ss_t* p, float sq) { const float fl = floorf(sq); const unsigned hi = (unsigned)fl, lo = (unsigned)((sq - fl) * 4294967296.0f); atomicAdd(p, ((ss_t)hi << 32) | (ss_t)lo); }
;     __device__ __forceinline__ void operator()(const f32x4 (&acc)[2][2][4][2], const Unit& u, int wr, int wc, int fr, int fq) const {
;     ...
;                 if (!OUT) { sq += __shfl_xor(sq, 16); sq += __shfl_xor(sq, 32); if (fq == 0) ss_add(ssq_out + row, sq); } }
.LBB0_1368:
	v_and_b32_e32 v5, 64, v208
	v_xor_b32_e32 v4, 16, v208
	v_add_u32_e32 v5, 64, v5
	v_cmp_lt_i32_e32 vcc, v4, v5
	v_xor_b32_e32 v6, 32, v208
	s_nop 0
	v_cndmask_b32_e32 v4, v208, v4, vcc
	v_lshlrev_b32_e32 v4, 2, v4
	v_mov_b32_e32 v4, v22
	s_nop 1
	v_permlane16_swap_b32_e32 v22, v4
	v_cmp_lt_i32_e32 vcc, v6, v5
	s_nop 0
	v_add_f32_e32 v4, v22, v4
	v_cndmask_b32_e32 v5, v208, v6, vcc
	v_lshlrev_b32_e32 v5, 2, v5
	v_mov_b32_e32 v5, v4
	s_nop 1
	v_permlane32_swap_b32_e32 v4, v5
	v_add_f32_e32 v6, v4, v5
	s_and_saveexec_b64 s[2:3], s[36:37]
	s_cbranch_execz .LBB0_1370
	s_nop 0
	v_floor_f32_e32 v8, v6
	v_sub_f32_e32 v6, v6, v8
	v_mul_f32_e32 v6, 0x4f800000, v6
	v_cvt_u32_f32_e32 v7, v8
	v_cvt_u32_f32_e32 v6, v6
	v_lshl_add_u64 v[4:5], v[182:183], 3, s[8:9]
	global_atomic_add_x2 v[4:5], v[6:7], off offset:1408
